# phase0: w_in transposes software-pipelined (next tile loads issued before current tile's LDS/store half); NSA cmp pass-1 loop QK woven into softmax
# speedup vs baseline: 1.5248x; 1.0024x over previous
; DI void phase_prep(const Params& P, unsigned char* smem) {
;     ...
;     float* tile = (float*)smem;
;     constexpr int I_WIN = 32 * (LDP / 64), I_W1 = 64 * 2, I_W2 = 2 * 2;
;     constexpr int NIT = I_WIN + 2 * I_W1 + 2 * I_W2 + 32;
;     for (int it = blockIdx.x; it < NIT; it += gridDim.x) {
;         int r = it;
;         if (r < I_WIN) { const int kb = r & 31, nb = r >> 5; transpose_tile(P.w_in, INDIM, P_winT, DM, kb * 64, nb * 64, 1, nullptr, tile); continue; } r -= I_WIN;
.LBB0_22:
	s_or_b64 exec, exec, s[4:5]
	s_cmpk_gt_i32 s6, 0x1ea7
	s_cbranch_scc1 .LBB0_54
	s_add_u32 s68, s30, 0x3ed08000
	s_addc_u32 s69, s31, 0
	v_lshlrev_b32_e32 v0, 5, v13
	v_ashrrev_i32_e32 v13, 31, v12
	s_add_u32 s70, s30, 0x3ed00000
	v_lshlrev_b64 v[6:7], 9, v[12:13]
	s_mov_b64 s[8:9], 0x40000
	s_addc_u32 s71, s31, 0
	v_lshl_add_u64 v[8:9], v[6:7], 0, s[8:9]
	s_mov_b64 s[8:9], 0x80000
	s_add_u32 s72, s30, 0x3ec00000
	v_lshl_add_u64 v[10:11], v[6:7], 0, s[8:9]
	s_mov_b64 s[8:9], 0xc0000
	s_addc_u32 s73, s31, 0
	v_cmp_eq_u32_e64 s[2:3], 0, v14
	v_lshl_add_u64 v[14:15], v[6:7], 0, s[8:9]
	s_mov_b64 s[8:9], 0x100000
	s_add_u32 s74, s30, 0x3eb00000
	v_lshl_add_u64 v[16:17], v[6:7], 0, s[8:9]
	s_mov_b64 s[8:9], 0x140000
	s_addc_u32 s75, s31, 0
	v_lshl_add_u64 v[18:19], v[6:7], 0, s[8:9]
	s_mov_b64 s[8:9], 0x180000
	s_add_u32 s76, s30, 0x3b000000
	v_mbcnt_hi_u32_b32 v38, -1, v173
	v_lshl_add_u64 v[20:21], v[6:7], 0, s[8:9]
	s_mov_b64 s[8:9], 0x1c0000
	s_addc_u32 s77, s31, 0
	s_lshl_b32 s0, s6, 5
	v_add_u32_e32 v37, 0, v0
	v_and_b32_e32 v0, 64, v38
	s_mov_b32 s97, s87
	s_mov_b32 s15, 0
	v_cmp_gt_i32_e64 s[4:5], 8, v12
	v_lshl_add_u32 v36, v12, 2, 0
	v_lshl_add_u64 v[22:23], v[6:7], 0, s[8:9]
	s_add_i32 s33, s33, 0xffff0bc0
	s_lshl_b32 s80, s10, 3
	s_add_i32 s81, s0, 0x7ffc2f80
	s_lshl_b32 s82, s10, 5
	s_lshl_b32 s83, s6, 6
	s_lshl_b32 s84, s10, 6
	s_lshl_b32 s85, s6, 1
	s_lshl_b32 s86, s10, 1
	s_movk_i32 s87, 0x1000
	s_movk_i32 s88, 0x2000
	s_movk_i32 s89, 0x3000
	s_mov_b32 s90, 0x3ed10000
	v_mov_b32_e32 v25, 0
	s_movk_i32 s91, 0x104
	s_movk_i32 s92, 0x1400
	s_movk_i32 s93, 0x3a20
	s_movk_i32 s94, 0x3a50
	s_mov_b32 s95, 0xe940
	v_add_u32_e32 v39, 64, v0
	v_xor_b32_e32 v40, 1, v38
	v_xor_b32_e32 v41, 2, v38
	v_xor_b32_e32 v42, 4, v38
	v_xor_b32_e32 v43, 8, v38
	v_xor_b32_e32 v44, 16, v38
	v_xor_b32_e32 v45, 32, v38
	s_mov_b32 s101, 0
	s_mov_b32 s96, s6
	s_branch .LBB0_26

; DI int opaque_tid() { int t = threadIdx.x; asm volatile("" : "+v"(t)); return t; }
; DI void transpose_tile(const float* src, int ldsrc, bf16_t* dst, int lddst, int k0, int n0, int mode, const float* rowscale, float* tile) {
;     const int tid = opaque_tid();
;     {
;         const int r = tid >> 4, c4 = (tid & 15) * 4;
; #pragma unroll
;         for (int q = 0; q < 2; ++q) {
;             const int rr = r + 32 * q; const int jd = n0 + c4; const int js = mode ? win_srccol(jd) : jd;
;             f32x4 v = {0.f, 0.f, 0.f, 0.f};
;             if (js >= 0) v = *(const f32x4*)(src + (size_t)(k0 + rr) * ldsrc + js);
;             if (rowscale) { const float sc = rowscale[k0 + rr]; v = v * sc; }
;             tile[rr * 65 + c4 + 0] = v[0]; tile[rr * 65 + c4 + 1] = v[1]; tile[rr * 65 + c4 + 2] = v[2]; tile[rr * 65 + c4 + 3] = v[3];
;         }
; DI void phase_prep(const Params& P, unsigned char* smem) {
;     ...
;     for (int it = blockIdx.x; it < NIT; it += gridDim.x) {
;         int r = it;
;         if (r < I_WIN) { const int kb = r & 31, nb = r >> 5; transpose_tile(P.w_in, INDIM, P_winT, DM, kb * 64, nb * 64, 1, nullptr, tile); continue; } r -= I_WIN;
.LBB0_48:
	s_andn2_b64 vcc, exec, s[8:9]
	s_cbranch_vccnz .LBB0_25
	v_mov_b32_e32 v26, v215
	v_lshlrev_b32_e32 v0, 2, v26
	v_and_b32_e32 v1, 60, v0
	v_ashrrev_i32_e32 v27, 4, v26
	s_and_b32 s78, s85, 0xffffffc0
	v_or_b32_e32 v0, s78, v1
	s_and_b32 s14, s83, 0x7c0
	s_cmpk_lt_u32 s85, 0x2a00
	v_add_u32_e32 v3, 0xfffff000, v0
	v_cmp_gt_u32_e64 s[8:9], s94, v0
	s_cselect_b64 vcc, -1, 0
	s_cmpk_lt_u32 s85, 0x3a00
	v_cndmask_b32_e64 v3, -1, v3, s[8:9]
	v_add_u32_e32 v4, 0xffffda00, v0
	v_cmp_gt_u32_e64 s[8:9], s93, v0
	v_add_u32_e32 v5, 0x50, v0
	v_add_u32_e32 v2, 32, v0
	v_cndmask_b32_e64 v3, v3, v4, s[8:9]
	s_cselect_b64 s[8:9], -1, 0
	s_nop 1
	v_cndmask_b32_e64 v3, v3, v5, s[8:9]
	v_cndmask_b32_e32 v2, v3, v2, vcc
	v_cmp_gt_i32_e32 vcc, s92, v0
	s_nop 1
	v_cndmask_b32_e32 v24, v2, v0, vcc
	v_cmp_lt_i32_e32 vcc, -1, v24
	v_lshl_add_u32 v136, v1, 2, 0
	v_mul_lo_u32 v28, v27, s91
	v_add_u32_e32 v28, v136, v28
	s_cmp_lg_u32 s101, 0
	s_cbranch_scc1 .Lp0_have
	v_mov_b32_e32 v112, 0
	v_mov_b32_e32 v113, 0
	v_mov_b32_e32 v114, 0
	v_mov_b32_e32 v115, 0
	v_mov_b32_e32 v120, 0
	v_mov_b32_e32 v121, 0
	v_mov_b32_e32 v122, 0
	v_mov_b32_e32 v123, 0
	s_and_saveexec_b64 s[8:9], vcc
	s_cbranch_execz .Lp0_nl0
	v_add_u32_e32 v4, s14, v27
	v_mov_b64_e32 v[116:117], s[16:17]
	v_mad_i64_i32 v[116:117], s[0:1], v4, s95, v[116:117]
	v_lshl_add_u64 v[116:117], v[24:25], 2, v[116:117]
	global_load_dwordx4 v[112:115], v[116:117], off
	v_add3_u32 v4, v27, s14, 32
	v_mov_b64_e32 v[118:119], s[16:17]
	v_mad_i64_i32 v[118:119], s[0:1], v4, s95, v[118:119]
	v_lshl_add_u64 v[118:119], v[24:25], 2, v[118:119]
	global_load_dwordx4 v[120:123], v[118:119], off
.Lp0_nl0:
	s_or_b64 exec, exec, s[8:9]
	s_waitcnt vmcnt(1)
	ds_write2_b32 v28, v112, v113 offset1:1
	ds_write2_b32 v28, v114, v115 offset0:2 offset1:3
	s_waitcnt vmcnt(0)
	v_add_u32_e32 v4, 0x2080, v28
	ds_write2_b32 v4, v120, v121 offset1:1
	v_add_u32_e32 v0, 0x2088, v28
	ds_write2_b32 v0, v122, v123 offset1:1
	s_branch .Lp0_written
.Lp0_have:
	s_waitcnt vmcnt(2)
	ds_write2_b32 v28, v112, v113 offset1:1
	ds_write2_b32 v28, v114, v115 offset0:2 offset1:3
	s_waitcnt vmcnt(1)
	v_add_u32_e32 v4, 0x2080, v28
	ds_write2_b32 v4, v120, v121 offset1:1
	v_add_u32_e32 v0, 0x2088, v28
	ds_write2_b32 v0, v122, v123 offset1:1
.Lp0_written:
	s_mov_b32 s101, 0
	s_add_i32 s98, s96, s10
	s_cmpk_gt_i32 s98, 0x1d7f
	s_cbranch_scc1 .Lp0_nopf
	s_mov_b32 s101, 1
	s_add_i32 s98, s83, s84
	s_add_i32 s99, s85, s86
	v_mov_b32_e32 v131, 0
	s_and_b32 s100, s99, 0xffffffc0
	v_or_b32_e32 v124, s100, v1
	s_and_b32 s98, s98, 0x7c0
	s_cmpk_lt_u32 s99, 0x2a00
	v_add_u32_e32 v125, 0xfffff000, v124
	v_cmp_gt_u32_e64 s[8:9], s94, v124
	s_cselect_b64 vcc, -1, 0
	s_cmpk_lt_u32 s99, 0x3a00
	v_cndmask_b32_e64 v125, -1, v125, s[8:9]
	v_add_u32_e32 v126, 0xffffda00, v124
	v_cmp_gt_u32_e64 s[8:9], s93, v124
	v_add_u32_e32 v127, 0x50, v124
	v_add_u32_e32 v128, 32, v124
	v_cndmask_b32_e64 v125, v125, v126, s[8:9]
	s_cselect_b64 s[8:9], -1, 0
	s_nop 1
	v_cndmask_b32_e64 v125, v125, v127, s[8:9]
	v_cndmask_b32_e32 v128, v125, v128, vcc
	v_cmp_gt_i32_e32 vcc, s92, v124
	s_nop 1
	v_cndmask_b32_e32 v130, v128, v124, vcc
	v_cmp_lt_i32_e32 vcc, -1, v130
	v_mov_b32_e32 v112, 0
	v_mov_b32_e32 v113, 0
	v_mov_b32_e32 v114, 0
	v_mov_b32_e32 v115, 0
	v_mov_b32_e32 v120, 0
	v_mov_b32_e32 v121, 0
	v_mov_b32_e32 v122, 0
	v_mov_b32_e32 v123, 0
	s_and_saveexec_b64 s[8:9], vcc
	s_cbranch_execz .Lp0_nl1
	v_add_u32_e32 v126, s98, v27
	v_mov_b64_e32 v[132:133], s[16:17]
	v_mad_i64_i32 v[132:133], s[0:1], v126, s95, v[132:133]
	v_lshl_add_u64 v[132:133], v[130:131], 2, v[132:133]
	global_load_dwordx4 v[112:115], v[132:133], off
	v_add3_u32 v126, v27, s98, 32
	v_mov_b64_e32 v[134:135], s[16:17]
	v_mad_i64_i32 v[134:135], s[0:1], v126, s95, v[134:135]
	v_lshl_add_u64 v[134:135], v[130:131], 2, v[134:135]
	global_load_dwordx4 v[120:123], v[134:135], off

; DI unsigned pk2(float lo, float hi) { f32x2 v = {lo, hi}; bf16x2_t b = __builtin_convertvector(v, bf16x2_t); return __builtin_bit_cast(unsigned, b); }
; #define LDS_BAR() do { asm volatile("s_waitcnt lgkmcnt(0)" ::: "memory"); __builtin_amdgcn_s_barrier(); asm volatile("" ::: "memory"); } while (0)
; DI void transpose_tile(const float* src, int ldsrc, bf16_t* dst, int lddst, int k0, int n0, int mode, const float* rowscale, float* tile) {
;     ...
;     LDS_BAR();
;     {
;         const int n = tid >> 3, k8 = (tid & 7) * 8;
;         u32x4 w;
;         w.x = pk2(tile[(k8 + 0) * 65 + n], tile[(k8 + 1) * 65 + n]); w.y = pk2(tile[(k8 + 2) * 65 + n], tile[(k8 + 3) * 65 + n]);
;         w.z = pk2(tile[(k8 + 4) * 65 + n], tile[(k8 + 5) * 65 + n]); w.w = pk2(tile[(k8 + 6) * 65 + n], tile[(k8 + 7) * 65 + n]);
;         *(u32x4*)(dst + (size_t)(n0 + n) * lddst + k0 + k8) = w;
;     }
;     LDS_BAR();
.Lp0_nopf:
	v_lshlrev_b32_e32 v0, 3, v26
	v_ashrrev_i32_e32 v24, 3, v26
	v_and_b32_e32 v28, 56, v0
	v_mul_u32_u24_e32 v0, 0x104, v28
	v_lshlrev_b32_e32 v1, 2, v24
	s_waitcnt lgkmcnt(0)
	s_barrier
	v_add3_u32 v4, 0, v0, v1
	ds_read2_b32 v[0:1], v4 offset1:65
	ds_read2_b32 v[2:3], v4 offset0:130 offset1:195
	v_add_u32_e32 v26, 0x400, v4
	ds_read2_b32 v[4:5], v26 offset0:4 offset1:69
	ds_read2_b32 v[26:27], v26 offset0:134 offset1:199
	s_lshl_b32 s14, s14, 1
	s_waitcnt lgkmcnt(3)
	v_cvt_pk_bf16_f32 v0, v0, v1
	s_waitcnt lgkmcnt(2)
	v_cvt_pk_bf16_f32 v1, v2, v3
	s_waitcnt lgkmcnt(1)
	v_cvt_pk_bf16_f32 v2, v4, v5
	v_add_u32_e32 v4, s78, v24
	v_ashrrev_i32_e32 v5, 31, v4
	v_lshlrev_b64 v[4:5], 12, v[4:5]
	v_lshl_add_u64 v[4:5], s[76:77], 0, v[4:5]
	v_lshl_add_u64 v[4:5], v[4:5], 0, s[14:15]
	v_lshlrev_b32_e32 v24, 1, v28
	s_waitcnt lgkmcnt(0)
	v_cvt_pk_bf16_f32 v3, v26, v27
	v_lshl_add_u64 v[4:5], v[4:5], 0, v[24:25]
	global_store_dwordx4 v[4:5], v[0:3], off
	s_waitcnt lgkmcnt(0)
	s_barrier
	s_branch .LBB0_25

; #define LAS __attribute__((address_space(3)))
; #define MFMA32(a, b, c) __builtin_amdgcn_mfma_f32_32x32x16_bf16((a), (b), (c), 0, 0, 0)
; #define CO_STEP2(list, n, i) do { \
;     if ((n) - 1 - (i) >= 1) asm volatile("s_waitcnt vmcnt(2)" ::: "memory"); else asm volatile("s_waitcnt vmcnt(0)" ::: "memory"); \
;     asm volatile("s_waitcnt lgkmcnt(0)" ::: "memory"); __builtin_amdgcn_s_barrier(); asm volatile("" ::: "memory"); \
;     if ((i) + 2 < (n)) co_issue(P, ring, ((i) + 2) & 3, (list)[(i) + 2], b, g, wave, lane); } while (0)
; #define CO_PIPE(MODE, REL, KB, RS) do { const bool rel_ = (REL); LAS unsigned char* sp_ = ring + (i & 3) * 16384; f32x16 Sn_; \
;     if (rel_) Sn_ = co_qk1(sp_, qf, ka); \
;     if (pend) co_finish<MODE>(Sp, pst, pkb, st, tq, prs, vb, hh); \
;     pend = rel_; if (rel_) { Sp = Sn_; pst = sp_; pkb = (KB); prs = (RS); } } while (0)
; DI f32x16 co_qk1(LAS unsigned char* st, const bf16x8 (&qf)[8], int ka_in) {
;     const int ka = ka_in;
;     f32x16 S;
; #pragma unroll
;     for (int i = 0; i < 16; ++i) S[i] = 0.f;
;     __builtin_amdgcn_s_setprio(1);
; #pragma unroll
;     for (int ks = 0; ks < 8; ++ks) { const bf16x8 a = *(const LAS bf16x8*)(st + (ka ^ (32 * ks))); S = MFMA32(a, qf[ks], S); }
;     __builtin_amdgcn_s_setprio(0);
;     return S;
; }
; DI void nsa_block_item(const Params& P, unsigned char* smem_g, int b, int g, int tb, int tid_in) {
;     ...
;     for (; i < nA; ++i) { CO_STEP2(list1, n1, i); const int kb_ = 32 * i; CO_PIPE(0, 16 * kb_ + 31 <= t0 + 3, kb_, true); }
.LBB0_422:
	s_cmp_le_i32 s77, s59
	s_cselect_b64 s[4:5], -1, 0
	s_and_b32 s0, s78, 0xc000
	s_add_i32 s16, s0, 0
	s_cmp_gt_i32 s77, s59
	s_cbranch_scc1 .LBB0_424
	s_andn2_b64 vcc, exec, s[8:9]
	s_cbranch_vccz .Lfs_cmp
	s_setprio 1
	v_add_u32_e32 v0, s16, v162
	ds_read_b128 v[2:5], v0
	v_add_u32_e32 v0, s16, v164
	ds_read_b128 v[6:9], v0
	v_add_u32_e32 v0, s16, v165
	s_waitcnt lgkmcnt(0)
	v_mfma_f32_32x32x16_bf16 v[96:111], v[2:5], v[112:115], 0
	ds_read_b128 v[2:5], v0
	v_add_u32_e32 v0, s16, v166
	v_mfma_f32_32x32x16_bf16 v[96:111], v[6:9], v[116:119], v[96:111]
	ds_read_b128 v[6:9], v0
	v_add_u32_e32 v0, s16, v167
	s_waitcnt lgkmcnt(0)
	v_mfma_f32_32x32x16_bf16 v[96:111], v[2:5], v[120:123], v[96:111]
	ds_read_b128 v[2:5], v0
	v_add_u32_e32 v0, s16, v168
	v_mfma_f32_32x32x16_bf16 v[96:111], v[6:9], v[124:127], v[96:111]
	ds_read_b128 v[6:9], v0
	v_add_u32_e32 v0, s16, v169
	s_waitcnt lgkmcnt(0)
	v_mfma_f32_32x32x16_bf16 v[96:111], v[2:5], v[128:131], v[96:111]
	ds_read_b128 v[2:5], v0
	v_add_u32_e32 v0, s16, v170
	v_mfma_f32_32x32x16_bf16 v[96:111], v[6:9], v[132:135], v[96:111]
	ds_read_b128 v[6:9], v0
	s_waitcnt lgkmcnt(0)
	v_mfma_f32_32x32x16_bf16 v[96:111], v[2:5], v[136:139], v[96:111]
	v_mfma_f32_32x32x16_bf16 v[96:111], v[6:9], v[140:143], v[96:111]
	s_setprio 0

; #define LAS __attribute__((address_space(3)))
; DI float xh_max(float x) { const unsigned u = __float_as_uint(x); const auto r = __builtin_amdgcn_permlane32_swap(u, u, false, false); return fmaxf(__uint_as_float(r[0]), __uint_as_float(r[1])); }
; DI float xh_sum(float x) { const unsigned u = __float_as_uint(x); const auto r = __builtin_amdgcn_permlane32_swap(u, u, false, false); return __uint_as_float(r[0]) + __uint_as_float(r[1]); }
; #define MFMA32(a, b, c) __builtin_amdgcn_mfma_f32_32x32x16_bf16((a), (b), (c), 0, 0, 0)
; DI f32x16 co_qk1(LAS unsigned char* st, const bf16x8 (&qf)[8], int ka_in) {
;     const int ka = ka_in;
;     f32x16 S;
; #pragma unroll
;     for (int i = 0; i < 16; ++i) S[i] = 0.f;
;     __builtin_amdgcn_s_setprio(1);
; #pragma unroll
;     for (int ks = 0; ks < 8; ++ks) { const bf16x8 a = *(const LAS bf16x8*)(st + (ka ^ (32 * ks))); S = MFMA32(a, qf[ks], S); }
;     __builtin_amdgcn_s_setprio(0);
;     return S;
; }
; template <int MODE>
; DI void co_finish(f32x16 S, LAS unsigned char* st, int key_base, AttnState& as, int tq, bool rowsel, int vb_in, int hh) {
;     const int vb = vb_in;
;     {
;         const int base = key_base + 4 * hh;
;         const int hi = (MODE == 0) ? (((tq - 31) >> 4) - base) : (tq - base);
;         const int lo = hi - 512;
; #pragma unroll
;         for (int i = 0; i < 16; ++i) { const int c = (i & 3) + 8 * (i >> 2); bool ok = (c <= hi); if (MODE == 2) ok = ok && (c > lo); if (MODE == 1) ok = ok && rowsel; S[i] = ok ? S[i] : -1e30f; }
;     }
;     float mx = S[0];
; #pragma unroll
;     for (int i = 1; i < 16; ++i) mx = fmaxf(mx, S[i]);
;     mx = xh_max(mx);
;     const float mxs = mx * SM_SCALE; const bool need = mxs > as.m + 8.f;
;     const float mnew = need ? mxs : as.m, muse = -fmaxf(mnew, -1e20f); float ps = 0.f;
; #pragma unroll
;     for (int i = 0; i < 16; ++i) { const float p = __builtin_amdgcn_exp2f(__builtin_fmaf(S[i], SM_SCALE, muse)); S[i] = p; ps += p; }
;     ps = xh_sum(ps);
;     if (__builtin_amdgcn_ballot_w64(need) != 0ull) {
;         const float alpha = __builtin_amdgcn_exp2f(as.m - mnew);
;         as.l *= alpha;
; #pragma unroll
;         for (int dt = 0; dt < 4; ++dt)
; #pragma unroll
;             for (int i = 0; i < 16; ++i) as.acc[dt][i] *= alpha;
;     }
;     as.l += ps; as.m = mnew;
.Lfs_cmp:
	v_add_u32_e32 v246, s16, v162
	ds_read_b128 v[238:241], v246
	v_add_u32_e32 v246, s16, v164
	ds_read_b128 v[242:245], v246
	v_add_u32_e32 v0, s80, v180
	v_cmp_lt_i32_e32 vcc, -1, v0
	s_nop 1
	v_cndmask_b32_e32 v3, v153, v16, vcc
	v_cmp_lt_i32_e32 vcc, 0, v0
	v_max_f32_e32 v2, v3, v3
	s_nop 0
	v_cndmask_b32_e32 v4, v153, v17, vcc
	v_cmp_lt_i32_e32 vcc, 1, v0
	s_nop 1
	v_cndmask_b32_e32 v5, v153, v18, vcc
	v_cmp_lt_i32_e32 vcc, 2, v0
	s_waitcnt lgkmcnt(1)
	v_mfma_f32_32x32x16_bf16 v[96:111], v[238:241], v[112:115], 0
	v_add_u32_e32 v246, s16, v165
	ds_read_b128 v[238:241], v246
	s_nop 1
	v_cndmask_b32_e32 v6, v153, v19, vcc
	v_cmp_lt_i32_e32 vcc, 7, v0
	s_nop 1
	v_cndmask_b32_e32 v7, v153, v20, vcc
	v_cmp_lt_i32_e32 vcc, 8, v0
	s_nop 1
	v_cndmask_b32_e32 v8, v153, v21, vcc
	v_cmp_lt_i32_e32 vcc, 9, v0
	s_nop 1
	v_cndmask_b32_e32 v9, v153, v22, vcc
	v_cmp_lt_i32_e32 vcc, 10, v0
	s_waitcnt lgkmcnt(1)
	v_mfma_f32_32x32x16_bf16 v[96:111], v[242:245], v[116:119], v[96:111]
	v_add_u32_e32 v246, s16, v166
	ds_read_b128 v[242:245], v246
	s_nop 1
	v_cndmask_b32_e32 v10, v153, v23, vcc
	v_cmp_lt_i32_e32 vcc, 15, v0
	s_nop 1
	v_cndmask_b32_e32 v11, v153, v24, vcc
	v_cmp_lt_i32_e32 vcc, 16, v0
	s_nop 1
	v_cndmask_b32_e32 v12, v153, v25, vcc
	v_cmp_lt_i32_e32 vcc, 17, v0
	s_nop 1
	v_cndmask_b32_e32 v13, v153, v26, vcc
	v_cmp_lt_i32_e32 vcc, 18, v0
	s_waitcnt lgkmcnt(1)
	v_mfma_f32_32x32x16_bf16 v[96:111], v[238:241], v[120:123], v[96:111]
	v_add_u32_e32 v246, s16, v167
	ds_read_b128 v[238:241], v246
	s_nop 1
	v_cndmask_b32_e32 v14, v153, v27, vcc
	v_cmp_lt_i32_e32 vcc, 23, v0
	s_nop 1
	v_cndmask_b32_e32 v15, v153, v28, vcc
	v_cmp_lt_i32_e32 vcc, 24, v0
	s_nop 1
	v_cndmask_b32_e32 v182, v153, v29, vcc
	v_cmp_lt_i32_e32 vcc, 25, v0
	s_nop 1
	v_cndmask_b32_e32 v183, v153, v30, vcc
	v_cmp_lt_i32_e32 vcc, 26, v0
	s_waitcnt lgkmcnt(1)
	v_mfma_f32_32x32x16_bf16 v[96:111], v[242:245], v[124:127], v[96:111]
	v_add_u32_e32 v246, s16, v168
	ds_read_b128 v[242:245], v246
	v_max_f32_e32 v0, v4, v4
	v_max_f32_e32 v0, v2, v0
	v_max3_f32 v0, v0, v5, v6
	v_max3_f32 v0, v0, v7, v8
	v_max3_f32 v0, v0, v9, v10
	v_max3_f32 v0, v0, v11, v12
	v_max3_f32 v0, v0, v13, v14
	v_cndmask_b32_e32 v184, v153, v31, vcc
	v_max3_f32 v0, v0, v15, v182
	v_max3_f32 v0, v0, v183, v184
	v_mov_b32_e32 v2, v0
	s_nop 1
	v_permlane32_swap_b32_e32 v0, v2
	s_waitcnt lgkmcnt(1)
	v_mfma_f32_32x32x16_bf16 v[96:111], v[238:241], v[128:131], v[96:111]
	v_add_u32_e32 v246, s16, v169
	ds_read_b128 v[238:241], v246
	v_max_f32_e32 v2, v2, v2
	v_max_f32_e32 v0, v0, v0
	v_max_f32_e32 v0, v0, v2
	v_mul_f32_e32 v0, 0x3e0293ee, v0
	v_add_f32_e32 v2, 0x41000000, v181
	v_cmp_gt_f32_e32 vcc, v0, v2
	s_nop 1
	v_cndmask_b32_e32 v2, v181, v0, vcc
	v_max_f32_e32 v0, v2, v2
	v_max_f32_e32 v185, 0xe0ad78ec, v0
	v_fma_f32 v0, v3, s52, -v185
	v_exp_f32_e32 v0, v0
	s_waitcnt lgkmcnt(1)
	v_mfma_f32_32x32x16_bf16 v[96:111], v[242:245], v[132:135], v[96:111]
	v_add_u32_e32 v246, s16, v170
	ds_read_b128 v[242:245], v246
	v_fma_f32 v3, v4, s52, -v185
	v_exp_f32_e32 v3, v3
	v_fma_f32 v4, v5, s52, -v185
	v_exp_f32_e32 v4, v4
	v_fma_f32 v5, v6, s52, -v185
	v_exp_f32_e32 v5, v5
	v_add_f32_e32 v6, 0, v0
	v_add_f32_e32 v6, v3, v6
	v_add_f32_e32 v6, v4, v6
	v_add_f32_e32 v186, v5, v6
	v_fma_f32 v6, v7, s52, -v185
	v_exp_f32_e32 v6, v6
	s_waitcnt lgkmcnt(1)
	v_mfma_f32_32x32x16_bf16 v[96:111], v[238:241], v[136:139], v[96:111]
	v_fma_f32 v7, v8, s52, -v185
	v_exp_f32_e32 v7, v7
	v_fma_f32 v8, v9, s52, -v185
	v_exp_f32_e32 v8, v8
	v_fma_f32 v9, v10, s52, -v185
	v_exp_f32_e32 v9, v9
	v_add_f32_e32 v10, v6, v186
	v_add_f32_e32 v10, v7, v10
	v_add_f32_e32 v10, v8, v10
	v_add_f32_e32 v186, v9, v10
	v_fma_f32 v10, v11, s52, -v185
	v_exp_f32_e32 v10, v10
	s_waitcnt lgkmcnt(0)
	v_mfma_f32_32x32x16_bf16 v[96:111], v[242:245], v[140:143], v[96:111]
	v_fma_f32 v11, v12, s52, -v185
	v_exp_f32_e32 v11, v11
	v_fma_f32 v12, v13, s52, -v185
	v_exp_f32_e32 v12, v12
	v_fma_f32 v13, v14, s52, -v185
	v_exp_f32_e32 v13, v13
	v_add_f32_e32 v14, v10, v186
	v_add_f32_e32 v14, v11, v14
	v_add_f32_e32 v14, v12, v14
	v_add_f32_e32 v186, v13, v14
	v_fma_f32 v14, v15, s52, -v185
	v_exp_f32_e32 v14, v14
	v_fma_f32 v15, v182, s52, -v185
	v_exp_f32_e32 v15, v15
	v_fma_f32 v182, v183, s52, -v185
	v_exp_f32_e32 v182, v182
	v_fma_f32 v183, v184, s52, -v185
	v_exp_f32_e32 v183, v183
	v_add_f32_e32 v184, v14, v186
	v_add_f32_e32 v184, v15, v184
	v_add_f32_e32 v184, v182, v184
	v_add_f32_e32 v184, v183, v184
	v_mov_b32_e32 v185, v184
	s_nop 1
	v_permlane32_swap_b32_e32 v184, v185
	s_cbranch_vccz .Lfs_cmp_427
	v_sub_f32_e32 v181, v181, v2
	v_exp_f32_e32 v186, v181
	s_nop 0
	v_mul_f32_e32 v179, v179, v186
	v_pk_mul_f32 v[94:95], v[94:95], v[186:187] op_sel_hi:[1,0]
	v_pk_mul_f32 v[92:93], v[92:93], v[186:187] op_sel_hi:[1,0]
	v_pk_mul_f32 v[90:91], v[90:91], v[186:187] op_sel_hi:[1,0]
	v_pk_mul_f32 v[88:89], v[88:89], v[186:187] op_sel_hi:[1,0]
	v_pk_mul_f32 v[86:87], v[86:87], v[186:187] op_sel_hi:[1,0]
	v_pk_mul_f32 v[84:85], v[84:85], v[186:187] op_sel_hi:[1,0]
	v_pk_mul_f32 v[82:83], v[82:83], v[186:187] op_sel_hi:[1,0]
	v_pk_mul_f32 v[80:81], v[80:81], v[186:187] op_sel_hi:[1,0]
	v_pk_mul_f32 v[78:79], v[78:79], v[186:187] op_sel_hi:[1,0]
	v_pk_mul_f32 v[76:77], v[76:77], v[186:187] op_sel_hi:[1,0]
	v_pk_mul_f32 v[74:75], v[74:75], v[186:187] op_sel_hi:[1,0]
	v_pk_mul_f32 v[72:73], v[72:73], v[186:187] op_sel_hi:[1,0]
	v_pk_mul_f32 v[70:71], v[70:71], v[186:187] op_sel_hi:[1,0]
	v_pk_mul_f32 v[68:69], v[68:69], v[186:187] op_sel_hi:[1,0]
	v_pk_mul_f32 v[66:67], v[66:67], v[186:187] op_sel_hi:[1,0]
	v_pk_mul_f32 v[64:65], v[64:65], v[186:187] op_sel_hi:[1,0]
	v_pk_mul_f32 v[62:63], v[62:63], v[186:187] op_sel_hi:[1,0]
	v_pk_mul_f32 v[60:61], v[60:61], v[186:187] op_sel_hi:[1,0]
	v_pk_mul_f32 v[58:59], v[58:59], v[186:187] op_sel_hi:[1,0]
	v_pk_mul_f32 v[56:57], v[56:57], v[186:187] op_sel_hi:[1,0]
	v_pk_mul_f32 v[54:55], v[54:55], v[186:187] op_sel_hi:[1,0]
	v_pk_mul_f32 v[52:53], v[52:53], v[186:187] op_sel_hi:[1,0]
	v_pk_mul_f32 v[50:51], v[50:51], v[186:187] op_sel_hi:[1,0]
	v_pk_mul_f32 v[48:49], v[48:49], v[186:187] op_sel_hi:[1,0]
	v_pk_mul_f32 v[46:47], v[46:47], v[186:187] op_sel_hi:[1,0]
	v_pk_mul_f32 v[44:45], v[44:45], v[186:187] op_sel_hi:[1,0]
	v_pk_mul_f32 v[42:43], v[42:43], v[186:187] op_sel_hi:[1,0]
	v_pk_mul_f32 v[40:41], v[40:41], v[186:187] op_sel_hi:[1,0]
	v_pk_mul_f32 v[38:39], v[38:39], v[186:187] op_sel_hi:[1,0]
	v_pk_mul_f32 v[36:37], v[36:37], v[186:187] op_sel_hi:[1,0]
	v_pk_mul_f32 v[34:35], v[34:35], v[186:187] op_sel_hi:[1,0]
	v_pk_mul_f32 v[32:33], v[32:33], v[186:187] op_sel_hi:[1,0]
; #define LAS __attribute__((address_space(3)))
; #define MFMA32(a, b, c) __builtin_amdgcn_mfma_f32_32x32x16_bf16((a), (b), (c), 0, 0, 0)
; DI bf16x8 cat44(s16x4 a, s16x4 b) { return __builtin_shufflevector(a, b, 0, 1, 2, 3, 4, 5, 6, 7); }
; template <int MODE>
; DI void co_finish(f32x16 S, LAS unsigned char* st, int key_base, AttnState& as, int tq, bool rowsel, int vb_in, int hh) {
;     ...
;     as.l += ps; as.m = mnew;
;     const bf16x8 p0 = pack8(S, 0), p1 = pack8(S, 1);
;     __builtin_amdgcn_s_setprio(1);
; #pragma unroll
;     for (int dt = 0; dt < 4; ++dt) {
;         LAS unsigned char* vp = st + 2048 * dt;
;         const bf16x8 a0 = cat44(*(const LAS s16x4*)(vp + (vb ^ 0)), *(const LAS s16x4*)(vp + (vb ^ 16))), a1 = cat44(*(const LAS s16x4*)(vp + (vb ^ 32)), *(const LAS s16x4*)(vp + (vb ^ 48)));
;         as.acc[dt] = MFMA32(a0, p0, as.acc[dt]); as.acc[dt] = MFMA32(a1, p1, as.acc[dt]);
;     }
;     __builtin_amdgcn_s_setprio(0);
; DI void xcd_barrier(const XcdBarrier& b) {
;     asm volatile("s_waitcnt vmcnt(0)" ::: "memory");
;     __syncthreads();
;     if (threadIdx.x == 0) {
;         unsigned* bar = b.bar;
;         __builtin_amdgcn_s_waitcnt(0);
;         unsigned nloc = b.st[0], nx = b.st[1];
;         if (nloc == 0u) { xcd_barrier_complete(bar, b.x, nloc, nx); b.st[0] = nloc; b.st[1] = nx; }
.Lfs_cmp_427:
	v_add_f32_e32 v181, v184, v185
	v_add_f32_e32 v179, v181, v179
	v_cvt_pk_bf16_f32 v184, v0, v3
	v_cvt_pk_bf16_f32 v185, v4, v5
	v_cvt_pk_bf16_f32 v186, v6, v7
	v_cvt_pk_bf16_f32 v187, v8, v9
	v_cvt_pk_bf16_f32 v4, v10, v11
	v_cvt_pk_bf16_f32 v5, v12, v13
	v_cvt_pk_bf16_f32 v6, v14, v15
	v_cvt_pk_bf16_f32 v7, v182, v183
	s_setprio 1
	v_add_u32_e32 v0, s62, v156
	v_add_u32_e32 v3, s62, v171
	ds_read2st64_b64 v[8:11], v0 offset0:16 offset1:20
	ds_read2st64_b64 v[12:15], v3 offset0:16 offset1:20
	v_add_u32_e32 v181, s62, v172
	v_add_u32_e32 v182, s62, v173
	ds_read2st64_b64 v[192:195], v181 offset0:16 offset1:20
	ds_read2st64_b64 v[196:199], v182 offset0:16 offset1:20
	s_waitcnt lgkmcnt(0)
	v_mov_b32_e32 v190, v12
	v_mov_b32_e32 v191, v13
	v_mov_b32_e32 v12, v10
	v_mov_b32_e32 v13, v11
	v_mov_b32_e32 v188, v8
	v_mov_b32_e32 v189, v9
	v_mfma_f32_32x32x16_bf16 v[64:79], v[12:15], v[184:187], v[64:79]
	ds_read2st64_b64 v[8:11], v0 offset0:24 offset1:28
	ds_read2st64_b64 v[12:15], v3 offset0:24 offset1:28
	v_mov_b32_e32 v202, v196
	v_mov_b32_e32 v203, v197
	v_mov_b32_e32 v196, v194
	v_mov_b32_e32 v197, v195
	v_mov_b32_e32 v200, v192
	v_mov_b32_e32 v201, v193
	v_mfma_f32_32x32x16_bf16 v[80:95], v[188:191], v[184:187], v[80:95]
	s_waitcnt lgkmcnt(0)
	v_mov_b32_e32 v188, v8
	v_mov_b32_e32 v189, v9
	v_mov_b32_e32 v190, v12
	v_mov_b32_e32 v191, v13
	v_mov_b32_e32 v12, v10
	v_mov_b32_e32 v13, v11
	ds_read2st64_b64 v[192:195], v181 offset0:24 offset1:28
	v_mfma_f32_32x32x16_bf16 v[64:79], v[196:199], v[4:7], v[64:79]
	ds_read2st64_b64 v[196:199], v182 offset0:24 offset1:28
	v_mfma_f32_32x32x16_bf16 v[48:63], v[188:191], v[184:187], v[48:63]
	v_mfma_f32_32x32x16_bf16 v[32:47], v[12:15], v[184:187], v[32:47]
	v_mfma_f32_32x32x16_bf16 v[80:95], v[200:203], v[4:7], v[80:95]
	s_waitcnt lgkmcnt(0)
	v_mov_b32_e32 v200, v192
	v_mov_b32_e32 v201, v193
	v_mov_b32_e32 v202, v196
	v_mov_b32_e32 v203, v197
	v_mov_b32_e32 v196, v194
	v_mov_b32_e32 v197, v195
	v_mfma_f32_32x32x16_bf16 v[48:63], v[200:203], v[4:7], v[48:63]
	s_nop 0
	v_mfma_f32_32x32x16_bf16 v[32:47], v[196:199], v[4:7], v[32:47]
	s_setprio 0
	s_andn2_b64 vcc, exec, s[4:5]
	s_cbranch_vccz .LBB0_429
	s_branch .LBB0_430
.LBB0_562:
	s_waitcnt vmcnt(0)
	s_barrier
	s_mov_b64 s[2:3], exec
	v_readlane_b32 s0, v236, 0
	v_readlane_b32 s1, v236, 1
	s_and_b64 s[0:1], s[2:3], s[0:1]
	s_mov_b64 exec, s[0:1]
	s_cbranch_execz .LBB0_614
	s_add_i32 s0, 0, 0x27ff0
	v_mov_b32_e32 v0, s0
	s_waitcnt vmcnt(0) expcnt(0) lgkmcnt(0)
	ds_read_b32 v2, v0
	s_add_i32 s0, 0, 0x27ff4
	v_mov_b32_e32 v0, s0
	ds_read_b32 v0, v0
	s_waitcnt lgkmcnt(1)
	v_cmp_ne_u32_e32 vcc, 0, v2
	s_cbranch_vccnz .LBB0_578
	s_add_u32 s4, s30, 0x3f732200
	s_addc_u32 s5, s31, 0
	s_add_u32 s8, s30, 0x3f732400
	s_addc_u32 s9, s31, 0
	s_add_u32 s16, s30, 0x3f732500
	s_addc_u32 s17, s31, 0
	s_add_u32 s18, s30, 0x3f732600
	s_addc_u32 s19, s31, 0
	s_add_u32 s20, s30, 0x3f732700
	s_addc_u32 s21, s31, 0
	s_add_u32 s22, s30, 0x3f732800
	s_addc_u32 s23, s31, 0
	s_add_u32 s24, s30, 0x3f732900
	s_addc_u32 s25, s31, 0
	s_add_u32 s26, s30, 0x3f732a00
	s_addc_u32 s27, s31, 0
	s_add_u32 s36, s30, 0x3f732b00
	s_addc_u32 s37, s31, 0
	s_add_u32 s38, s30, 0x3f732c00
	s_addc_u32 s39, s31, 0
	s_add_u32 s40, s30, 0x3f732d00
	s_addc_u32 s41, s31, 0
	s_add_u32 s42, s30, 0x3f732e00
	s_addc_u32 s43, s31, 0
	s_add_u32 s44, s30, 0x3f732f00
	s_addc_u32 s45, s31, 0
	s_add_u32 s46, s30, 0x3f733000
	s_addc_u32 s47, s31, 0
	s_add_u32 s48, s30, 0x3f733100
	s_addc_u32 s49, s31, 0
	s_add_u32 s50, s30, 0x3f733200
	s_addc_u32 s51, s31, 0
	s_mul_i32 s33, s11, s87
	s_add_u32 s52, s30, 0x3f733300
	s_mul_i32 s33, s33, s10
	s_addc_u32 s53, s31, 0
	s_mov_b32 s60, 1
	v_mov_b32_e32 v16, 0
	s_branch .LBB0_566

; #define LAS __attribute__((address_space(3)))
; template <int LO, int HI>
; __global__ void __launch_bounds__(512) fwd_kernel(Params P) {
;     extern __shared__ __attribute__((aligned(16))) unsigned char smem[];
;     if constexpr (HI - LO > 1) {
;         cg::grid_group grid = cg::this_grid();
;         if (P.ws == nullptr) grid.sync();
;         volatile LAS unsigned* xst = (volatile LAS unsigned*)((LAS unsigned char*)smem + (LDS_BYTES - 16));
;         if (threadIdx.x == 0) { xst[0] = 0u; xst[1] = 0u; }
;         __syncthreads();
;         const XcdBarrier xb = xcd_barrier_post((unsigned*)(P.ws + WS_BAR), xst);
;         run_phase<0>(P, smem); xcd_barrier(xb);
;         run_phase<1>(P, smem); xcd_barrier(xb);
;         run_phase<6>(P, smem); xcd_barrier(xb);
;         run_phase<2>(P, smem); xcd_barrier(xb);
;         run_phase<3>(P, smem); xcd_barrier(xb);
;         run_phase<4>(P, smem); xcd_barrier(xb);
;         run_phase<5>(P, smem);
;     } else {
;         run_phase<LO>(P, smem);
;     }
; }
	.amdhsa_kernel _Z10fwd_kernelILi0ELi6EEv7ParamsK
		.amdhsa_group_segment_fixed_size 0
		.amdhsa_private_segment_fixed_size 0
		.amdhsa_kernarg_size 464
		.amdhsa_user_sgpr_count 2
		.amdhsa_user_sgpr_dispatch_ptr 0
		.amdhsa_user_sgpr_queue_ptr 0
		.amdhsa_user_sgpr_kernarg_segment_ptr 1
		.amdhsa_user_sgpr_dispatch_id 0
		.amdhsa_user_sgpr_kernarg_preload_length 0
		.amdhsa_user_sgpr_kernarg_preload_offset 0
		.amdhsa_user_sgpr_private_segment_size 0
		.amdhsa_uses_dynamic_stack 0
		.amdhsa_enable_private_segment 0
		.amdhsa_system_sgpr_workgroup_id_x 1
		.amdhsa_system_sgpr_workgroup_id_y 0
		.amdhsa_system_sgpr_workgroup_id_z 0
		.amdhsa_system_sgpr_workgroup_info 0
		.amdhsa_system_vgpr_workitem_id 2
		.amdhsa_next_free_vgpr 256
		.amdhsa_next_free_sgpr 102
		.amdhsa_accum_offset 256
		.amdhsa_reserve_vcc 1
		.amdhsa_float_round_mode_32 0
		.amdhsa_float_round_mode_16_64 0
		.amdhsa_float_denorm_mode_32 3
		.amdhsa_float_denorm_mode_16_64 3
		.amdhsa_dx10_clamp 1
		.amdhsa_ieee_mode 1
		.amdhsa_fp16_overflow 0
		.amdhsa_tg_split 0
		.amdhsa_exception_fp_ieee_invalid_op 0
		.amdhsa_exception_fp_denorm_src 0
		.amdhsa_exception_fp_ieee_div_zero 0
		.amdhsa_exception_fp_ieee_overflow 0
		.amdhsa_exception_fp_ieee_underflow 0
		.amdhsa_exception_fp_ieee_inexact 0
		.amdhsa_exception_int_div_zero 0
	.end_amdhsa_kernel

; template <int LO, int HI>
; __global__ void __launch_bounds__(512) fwd_kernel(Params P) {
;     extern __shared__ __attribute__((aligned(16))) unsigned char smem[];
amdhsa.kernels:
  - .agpr_count:     0
    .args:
      - .offset:         0
        .size:           208
        .value_kind:     by_value
      - .offset:         208
        .size:           4
        .value_kind:     hidden_block_count_x
      - .offset:         212
        .size:           4
        .value_kind:     hidden_block_count_y
      - .offset:         216
        .size:           4
        .value_kind:     hidden_block_count_z
      - .offset:         220
        .size:           2
        .value_kind:     hidden_group_size_x
      - .offset:         222
        .size:           2
        .value_kind:     hidden_group_size_y
      - .offset:         224
        .size:           2
        .value_kind:     hidden_group_size_z
      - .offset:         226
        .size:           2
        .value_kind:     hidden_remainder_x
      - .offset:         228
        .size:           2
        .value_kind:     hidden_remainder_y
      - .offset:         230
        .size:           2
        .value_kind:     hidden_remainder_z
      - .offset:         248
        .size:           8
        .value_kind:     hidden_global_offset_x
      - .offset:         256
        .size:           8
        .value_kind:     hidden_global_offset_y
      - .offset:         264
        .size:           8
        .value_kind:     hidden_global_offset_z
      - .offset:         272
        .size:           2
        .value_kind:     hidden_grid_dims
      - .offset:         296
        .size:           8
        .value_kind:     hidden_multigrid_sync_arg
      - .offset:         328
        .size:           4
        .value_kind:     hidden_dynamic_lds_size
    .group_segment_fixed_size: 0
    .kernarg_segment_align: 8
    .kernarg_segment_size: 464
    .language:       OpenCL C
    .language_version:
      - 2
      - 0
    .max_flat_workgroup_size: 512
    .name:           _Z10fwd_kernelILi0ELi6EEv7ParamsK
    .private_segment_fixed_size: 0
    .sgpr_count:     108
    .sgpr_spill_count: 3
    .symbol:         _Z10fwd_kernelILi0ELi6EEv7ParamsK.kd
    .uniform_work_group_size: 1
    .uses_dynamic_stack: false
    .vgpr_count:     256
    .vgpr_spill_count: 0
    .wavefront_size: 64
